# P1 tile order through a 38-entry permutation table (spill VGPR lanes): per-CU epilogue load max 4.6 -> 4.1 silu units, late panels kept in late positions
# baseline (speedup 1.0000x reference)
; #define LAS __attribute__((address_space(3)))
; __device__ __forceinline__ int fresh_tid() { int t = threadIdx.x; asm volatile("" : "+v"(t)); return t; }
; __device__ __forceinline__ Frame make_frame(LAS unsigned char* lds) {
;     Frame F; F.lds = lds;
;     F.tid = fresh_tid(); F.lane = F.tid & 63; F.wave = __builtin_amdgcn_readfirstlane(F.tid >> 6);
;     F.G = gridDim.x; { const int bx = blockIdx.x; F.vcu = (F.G % 8 == 0) ? (bx % 8) * (F.G / 8) + bx / 8 : bx; }
.LBB0_5:
	s_or_b64 exec, exec, s[4:5]
	v_writelane_b32 v255, 7, 8
	v_writelane_b32 v255, 5, 9
	v_writelane_b32 v255, 10, 10
	v_writelane_b32 v255, 32, 11
	v_writelane_b32 v255, 3, 12
	v_writelane_b32 v255, 27, 13
	v_writelane_b32 v255, 35, 14
	v_writelane_b32 v255, 30, 15
	v_writelane_b32 v255, 28, 16
	v_writelane_b32 v255, 31, 17
	v_writelane_b32 v255, 37, 18
	v_writelane_b32 v255, 25, 19
	v_writelane_b32 v255, 20, 20
	v_writelane_b32 v255, 19, 21
	v_writelane_b32 v255, 22, 22
	v_writelane_b32 v255, 13, 23
	v_writelane_b32 v255, 15, 24
	v_writelane_b32 v255, 12, 25
	v_writelane_b32 v255, 24, 26
	v_writelane_b32 v255, 0, 27
	v_writelane_b32 v255, 6, 28
	v_writelane_b32 v255, 4, 29
	v_writelane_b32 v255, 33, 30
	v_writelane_b32 v255, 1, 31
	v_writelane_b32 v255, 9, 32
	v_writelane_b32 v255, 34, 33
	v_writelane_b32 v255, 29, 34
	v_writelane_b32 v255, 2, 35
	v_writelane_b32 v255, 36, 36
	v_writelane_b32 v255, 8, 37
	v_writelane_b32 v255, 18, 38
	v_writelane_b32 v255, 21, 39
	v_writelane_b32 v255, 14, 40
	v_writelane_b32 v255, 26, 41
	v_writelane_b32 v255, 17, 42
	v_writelane_b32 v255, 23, 43
	v_writelane_b32 v255, 16, 44
	v_writelane_b32 v255, 11, 45
	v_mov_b32_e32 v7, v0
	s_load_dword s3, s[0:1], 0xb8
	s_add_u32 s84, s0, 0xb8
	s_addc_u32 s85, s1, 0
	v_readfirstlane_b32 s4, v7
	s_mov_b32 s12, s2
	s_waitcnt lgkmcnt(0)
	s_and_b32 s5, s3, 7
	s_cmp_eq_u32 s5, 0
	s_cselect_b64 s[70:71], -1, 0
	s_cmp_lg_u32 s5, 0
	s_cbranch_scc1 .LBB0_7
	s_ashr_i32 s6, s2, 31
	s_lshr_b32 s6, s6, 29
	s_add_i32 s6, s2, s6
	s_and_b32 s7, s6, -8
	s_ashr_i32 s5, s3, 3
	s_sub_i32 s7, s2, s7
	s_mul_i32 s5, s5, s7
	s_ashr_i32 s6, s6, 3
	s_add_i32 s12, s5, s6

;     __device__ __forceinline__ bool next(int i, Unit& u) const {
;     ...
;         if (L < G1_SPECIAL) { u.pm = MP / 256 + (L >> 3); u.pn = 30 + (L & 7); u.kind = 4; }
;         else if ((L -= G1_SPECIAL) < G1_PROMPT) { int pm, pn; pg8::tile_order(L, MP / 256, G1_NN, pm, pn); u.pm = pm; u.pn = pn; }
.LBB0_124:
	s_and_b64 vcc, exec, s[18:19]
	s_cbranch_vccz .LBB0_126
	s_and_b32 s4, s2, 7
	s_add_i32 s5, s2, 0xfff0
	s_mulk_i32 s4, 0x98
	s_bfe_u32 s5, s5, 0xd0003
	s_add_i32 s4, s5, s4
	s_mul_i32 s5, s4, 0x6bcb
	s_lshr_b32 s5, s5, 23
	s_lshl_b32 s13, s5, 3
	s_and_b32 s16, s13, 0xfff8
	s_sub_i32 s16, 32, s16
	s_mulk_i32 s5, 0x130
	s_min_u32 s16, s16, 8
	s_sub_i32 s17, s4, s5
	s_and_b32 s4, s17, 0xffff
	v_cvt_f32_ubyte0_e32 v2, s16
	v_cvt_f32_u32_e32 v1, s4
	v_rcp_iflag_f32_e32 v3, v2
	s_mov_b32 s81, 0
	v_mul_f32_e32 v3, v1, v3
	v_trunc_f32_e32 v3, v3
	v_cvt_u32_f32_e32 v4, v3
	v_fma_f32 v1, -v3, v2, v1
	v_cmp_ge_f32_e64 s[4:5], |v1|, v2
	s_cmp_lg_u64 s[4:5], 0
	v_readfirstlane_b32 s18, v4
	s_addc_u32 s4, s18, 0
	s_and_b32 s62, s4, 0xffff
	s_mul_i32 s4, s4, s16
	s_sub_i32 s4, s17, s4
	s_add_i32 s4, s4, s13
	s_and_b32 s4, s4, 0xffff
	s_add_i32 s99, s62, 8
	s_nop 0
	v_readlane_b32 s62, v255, s99
	s_mov_b64 s[16:17], -1

;     __device__ __forceinline__ bool next(int i, Unit& u) const {
;         int L = i * G + c; if (L >= G1_ALL) return false;
;         u.nt = DM / 64; u.kind = 0;
;         if (L < G1_SPECIAL) { u.pm = MP / 256 + (L >> 3); u.pn = 30 + (L & 7); u.kind = 4; }
;         else if ((L -= G1_SPECIAL) < G1_PROMPT) { int pm, pn; pg8::tile_order(L, MP / 256, G1_NN, pm, pn); u.pm = pm; u.pn = pn; }
.LBB0_150:
	s_and_b32 s6, s5, 7
	s_add_i32 s13, s5, 0xfff0
	s_mulk_i32 s6, 0x98
	s_bfe_u32 s13, s13, 0xd0003
	s_add_i32 s13, s13, s6
	s_and_b32 s6, s13, 0xffff
	s_mul_i32 s6, s6, 0xd795
	s_lshr_b32 s6, s6, 24
	s_lshl_b32 s61, s6, 3
	s_sub_i32 s58, 32, s61
	s_mulk_i32 s6, 0x130
	s_min_u32 s63, s58, 8
	s_sub_i32 s6, s13, s6
	s_and_b32 s13, s6, 0xffff
	v_cvt_f32_ubyte0_e32 v3, s63
	v_cvt_f32_u32_e32 v2, s13
	v_rcp_iflag_f32_e32 v4, v3
	s_mov_b32 s13, 0
	s_mov_b64 s[70:71], -1
	v_mul_f32_e32 v4, v2, v4
	v_trunc_f32_e32 v4, v4
	v_cvt_u32_f32_e32 v5, v4
	v_fma_f32 v2, -v4, v3, v2
	v_cmp_ge_f32_e64 s[58:59], |v2|, v3
	s_cmp_lg_u64 s[58:59], 0
	v_readfirstlane_b32 s60, v5
	s_addc_u32 s58, s60, 0
	s_and_b32 s60, s58, 0xffff
	s_mul_i32 s58, s58, s63
	s_sub_i32 s6, s6, s58
	s_add_i32 s6, s6, s61
	s_and_b32 s58, s6, 0xffff
	s_add_i32 s99, s60, 8
	s_nop 0
	v_readlane_b32 s60, v255, s99
